# strategy 7.3: LRU gate tile loaded and stored with 16-byte accesses through a per-wave LDS transpose (was 32 two-byte VMEM ops per lane per tile)
# baseline (speedup 1.0000x reference)
.LBB0_1093:
	s_lshl_b32 s98, s10, 12
	s_add_i32 s98, s98, 0x1c000
	v_lshl_add_u32 v163, v220, 4, s98
	v_lshl_add_u32 v248, v220, 1, s98
	v_add_u32_e32 v249, 0x800, v248
	s_waitcnt vmcnt(0)
	ds_write_b128 v163, v[152:155]
	ds_write_b128 v163, v[156:159] offset:1024
	s_waitcnt lgkmcnt(0)
	ds_read_u16 v163, v248
	ds_read_u16 v162, v248 offset:128
	ds_read_u16 v161, v248 offset:256
	ds_read_u16 v160, v248 offset:384
	ds_read_u16 v159, v248 offset:512
	ds_read_u16 v158, v248 offset:640
	ds_read_u16 v157, v248 offset:768
	ds_read_u16 v156, v248 offset:896
	ds_read_u16 v155, v248 offset:1024
	ds_read_u16 v154, v248 offset:1152
	ds_read_u16 v153, v248 offset:1280
	ds_read_u16 v152, v248 offset:1408
	ds_read_u16 v151, v248 offset:1536
	ds_read_u16 v112, v248 offset:1664
	ds_read_u16 v109, v248 offset:1792
	ds_read_u16 v107, v248 offset:1920
	s_waitcnt lgkmcnt(0)
	s_waitcnt vmcnt(15)
	v_lshlrev_b32_e32 v163, 16, v163
	v_mul_f32_e32 v165, 0x3d372713, v163
	v_mul_f32_e32 v165, v165, v163
	v_fma_f32 v165, v165, v163, v163
	v_mul_f32_e32 v165, 0x3fcc422a, v165
	v_mul_f32_e32 v165, 0xbfb8aa3b, v165
	v_exp_f32_e32 v165, v165
	s_add_i32 s11, s11, 1
	s_cmp_lg_u32 s11, 16
	v_add_f32_e32 v165, 1.0, v165
	v_rcp_f32_e32 v165, v165
	s_waitcnt lgkmcnt(0)
	v_fma_f32 v111, v110, v182, v166
	v_mul_f32_e32 v163, v165, v163
	v_mul_f32_e32 v111, v163, v111
	v_cvt_pk_bf16_f32 v111, v111, v113
	ds_write_b16 v249, v111
	s_waitcnt vmcnt(15)
	v_lshlrev_b32_e32 v111, 16, v162
	v_mul_f32_e32 v162, 0x3d372713, v111
	v_mul_f32_e32 v162, v162, v111
	v_fma_f32 v162, v162, v111, v111
	v_mul_f32_e32 v162, 0x3fcc422a, v162
	v_mul_f32_e32 v162, 0xbfb8aa3b, v162
	v_exp_f32_e32 v162, v162
	s_nop 0
	v_add_f32_e32 v162, 1.0, v162
	v_rcp_f32_e32 v162, v162
	v_fma_f32 v66, v110, v183, v167
	v_mul_f32_e32 v111, v162, v111
	v_mul_f32_e32 v66, v111, v66
	v_cvt_pk_bf16_f32 v66, v66, v113
	ds_write_b16 v249, v66 offset:128
	s_waitcnt vmcnt(15)
	v_lshlrev_b32_e32 v86, 16, v161
	v_mul_f32_e32 v87, 0x3d372713, v86
	v_mul_f32_e32 v87, v87, v86
	v_fma_f32 v87, v87, v86, v86
	v_mul_f32_e32 v87, 0x3fcc422a, v87
	v_mul_f32_e32 v87, 0xbfb8aa3b, v87
	v_exp_f32_e32 v87, v87
	s_nop 0
	v_add_f32_e32 v87, 1.0, v87
	v_rcp_f32_e32 v87, v87
	v_fma_f32 v66, v110, v184, v168
	v_mul_f32_e32 v86, v87, v86
	v_mul_f32_e32 v66, v86, v66
	v_cvt_pk_bf16_f32 v66, v66, v113
	ds_write_b16 v249, v66 offset:256
	s_waitcnt vmcnt(15)
	v_lshlrev_b32_e32 v84, 16, v160
	v_mul_f32_e32 v85, 0x3d372713, v84
	v_mul_f32_e32 v85, v85, v84
	v_fma_f32 v85, v85, v84, v84
	v_mul_f32_e32 v85, 0x3fcc422a, v85
	v_mul_f32_e32 v85, 0xbfb8aa3b, v85
	v_exp_f32_e32 v85, v85
	s_nop 0
	v_add_f32_e32 v85, 1.0, v85
	v_rcp_f32_e32 v85, v85
	v_fma_f32 v66, v110, v185, v169
	v_mul_f32_e32 v84, v85, v84
	v_mul_f32_e32 v66, v84, v66
	v_cvt_pk_bf16_f32 v66, v66, v113
	ds_write_b16 v249, v66 offset:384
	s_waitcnt vmcnt(15)
	v_lshlrev_b32_e32 v82, 16, v159
	v_mul_f32_e32 v83, 0x3d372713, v82
	v_mul_f32_e32 v83, v83, v82
	v_fma_f32 v83, v83, v82, v82
	v_mul_f32_e32 v83, 0x3fcc422a, v83
	v_mul_f32_e32 v83, 0xbfb8aa3b, v83
	v_exp_f32_e32 v83, v83
	s_nop 0
	v_add_f32_e32 v83, 1.0, v83
	v_rcp_f32_e32 v83, v83
	v_fma_f32 v66, v110, v186, v170
	v_mul_f32_e32 v82, v83, v82
	v_mul_f32_e32 v66, v82, v66
	v_cvt_pk_bf16_f32 v66, v66, v113
	ds_write_b16 v249, v66 offset:512
	s_waitcnt vmcnt(15)
	v_lshlrev_b32_e32 v80, 16, v158
	v_mul_f32_e32 v81, 0x3d372713, v80
	v_mul_f32_e32 v81, v81, v80
	v_fma_f32 v81, v81, v80, v80
	v_mul_f32_e32 v81, 0x3fcc422a, v81
	v_mul_f32_e32 v81, 0xbfb8aa3b, v81
	v_exp_f32_e32 v81, v81
	s_nop 0
	v_add_f32_e32 v81, 1.0, v81
	v_rcp_f32_e32 v81, v81
	v_fma_f32 v66, v110, v187, v171
	v_mul_f32_e32 v80, v81, v80
	v_mul_f32_e32 v66, v80, v66
	v_cvt_pk_bf16_f32 v66, v66, v113
	ds_write_b16 v249, v66 offset:640
	s_waitcnt vmcnt(15)
	v_lshlrev_b32_e32 v78, 16, v157
	v_mul_f32_e32 v79, 0x3d372713, v78
	v_mul_f32_e32 v79, v79, v78
	v_fma_f32 v79, v79, v78, v78
	v_mul_f32_e32 v79, 0x3fcc422a, v79
	v_mul_f32_e32 v79, 0xbfb8aa3b, v79
	v_exp_f32_e32 v79, v79
	s_nop 0
	v_add_f32_e32 v79, 1.0, v79
	v_rcp_f32_e32 v79, v79
	v_fma_f32 v66, v110, v188, v172
	v_mul_f32_e32 v78, v79, v78
	v_mul_f32_e32 v66, v78, v66
	v_cvt_pk_bf16_f32 v66, v66, v113
	ds_write_b16 v249, v66 offset:768
	s_waitcnt vmcnt(15)
	v_lshlrev_b32_e32 v76, 16, v156
	v_mul_f32_e32 v77, 0x3d372713, v76
	v_mul_f32_e32 v77, v77, v76
	v_fma_f32 v77, v77, v76, v76
	v_mul_f32_e32 v77, 0x3fcc422a, v77
	v_mul_f32_e32 v77, 0xbfb8aa3b, v77
	v_exp_f32_e32 v77, v77
	s_nop 0
	v_add_f32_e32 v77, 1.0, v77
	v_rcp_f32_e32 v77, v77
	v_fma_f32 v66, v110, v189, v173
	v_mul_f32_e32 v76, v77, v76
	v_mul_f32_e32 v66, v76, v66
	v_cvt_pk_bf16_f32 v66, v66, v113
	ds_write_b16 v249, v66 offset:896
	s_waitcnt vmcnt(15)
	v_lshlrev_b32_e32 v74, 16, v155
	v_mul_f32_e32 v75, 0x3d372713, v74
	v_mul_f32_e32 v75, v75, v74
	v_fma_f32 v75, v75, v74, v74
	v_mul_f32_e32 v75, 0x3fcc422a, v75
	v_mul_f32_e32 v75, 0xbfb8aa3b, v75
	v_exp_f32_e32 v75, v75
	s_nop 0
	v_add_f32_e32 v75, 1.0, v75
	v_rcp_f32_e32 v75, v75
	v_fma_f32 v66, v110, v208, v174
	v_mul_f32_e32 v74, v75, v74
	v_mul_f32_e32 v66, v74, v66
	v_cvt_pk_bf16_f32 v66, v66, v113
	ds_write_b16 v249, v66 offset:1024
	s_waitcnt vmcnt(15)
	v_lshlrev_b32_e32 v72, 16, v154
	v_mul_f32_e32 v73, 0x3d372713, v72
	v_mul_f32_e32 v73, v73, v72
	v_fma_f32 v73, v73, v72, v72
	v_mul_f32_e32 v73, 0x3fcc422a, v73
	v_mul_f32_e32 v73, 0xbfb8aa3b, v73
	v_exp_f32_e32 v73, v73
	s_nop 0
	v_add_f32_e32 v73, 1.0, v73
	v_rcp_f32_e32 v73, v73
	v_fma_f32 v66, v110, v209, v175
	v_mul_f32_e32 v72, v73, v72
	v_mul_f32_e32 v66, v72, v66
	v_cvt_pk_bf16_f32 v66, v66, v113
	ds_write_b16 v249, v66 offset:1152
	s_waitcnt vmcnt(15)
	v_lshlrev_b32_e32 v70, 16, v153
	v_mul_f32_e32 v71, 0x3d372713, v70
	v_mul_f32_e32 v71, v71, v70
	v_fma_f32 v71, v71, v70, v70
	v_mul_f32_e32 v71, 0x3fcc422a, v71
	v_mul_f32_e32 v71, 0xbfb8aa3b, v71
	v_exp_f32_e32 v71, v71
	s_nop 0
	v_add_f32_e32 v71, 1.0, v71
	v_rcp_f32_e32 v71, v71
	v_fma_f32 v66, v110, v210, v176
	v_mul_f32_e32 v70, v71, v70
	v_mul_f32_e32 v66, v70, v66
	v_cvt_pk_bf16_f32 v66, v66, v113
	ds_write_b16 v249, v66 offset:1280
	s_waitcnt vmcnt(15)
	v_lshlrev_b32_e32 v68, 16, v152
	v_mul_f32_e32 v69, 0x3d372713, v68
	v_mul_f32_e32 v69, v69, v68
	v_fma_f32 v69, v69, v68, v68
	v_mul_f32_e32 v69, 0x3fcc422a, v69
	v_mul_f32_e32 v69, 0xbfb8aa3b, v69
	v_exp_f32_e32 v69, v69
	s_nop 0
	v_add_f32_e32 v69, 1.0, v69
	v_rcp_f32_e32 v69, v69
	v_fma_f32 v66, v110, v211, v177
	v_mul_f32_e32 v68, v69, v68
	v_mul_f32_e32 v66, v68, v66
	v_cvt_pk_bf16_f32 v66, v66, v113
	ds_write_b16 v249, v66 offset:1408
	s_waitcnt vmcnt(15)
	v_lshlrev_b32_e32 v66, 16, v151
	v_mul_f32_e32 v67, 0x3d372713, v66
	v_mul_f32_e32 v67, v67, v66
	v_fma_f32 v67, v67, v66, v66
	v_mul_f32_e32 v67, 0x3fcc422a, v67
	v_mul_f32_e32 v67, 0xbfb8aa3b, v67
	v_exp_f32_e32 v67, v67
	s_nop 0
	v_add_f32_e32 v67, 1.0, v67
	v_rcp_f32_e32 v67, v67
	v_fma_f32 v64, v110, v212, v178
	v_mul_f32_e32 v66, v67, v66
	v_mul_f32_e32 v64, v66, v64
	v_cvt_pk_bf16_f32 v64, v64, v113
	ds_write_b16 v249, v64 offset:1536
	s_waitcnt vmcnt(15)
	v_lshlrev_b32_e32 v64, 16, v112
	v_mul_f32_e32 v65, 0x3d372713, v64
	v_mul_f32_e32 v65, v65, v64
	v_fma_f32 v65, v65, v64, v64
	v_mul_f32_e32 v65, 0x3fcc422a, v65
	v_mul_f32_e32 v65, 0xbfb8aa3b, v65
	v_exp_f32_e32 v65, v65
	s_nop 0
	v_add_f32_e32 v65, 1.0, v65
	v_rcp_f32_e32 v65, v65
	v_fma_f32 v62, v110, v213, v179
	v_mul_f32_e32 v64, v65, v64
	v_mul_f32_e32 v62, v64, v62
	v_cvt_pk_bf16_f32 v62, v62, v113
	ds_write_b16 v249, v62 offset:1664
	s_waitcnt vmcnt(15)
	v_lshlrev_b32_e32 v62, 16, v109
	v_mul_f32_e32 v63, 0x3d372713, v62
	v_mul_f32_e32 v63, v63, v62
	v_fma_f32 v63, v63, v62, v62
	v_mul_f32_e32 v63, 0x3fcc422a, v63
	v_mul_f32_e32 v63, 0xbfb8aa3b, v63
	v_exp_f32_e32 v63, v63
	s_nop 0
	v_add_f32_e32 v63, 1.0, v63
	v_rcp_f32_e32 v63, v63
	v_fma_f32 v60, v110, v252, v180
	v_mul_f32_e32 v62, v63, v62
	v_mul_f32_e32 v60, v62, v60
	v_cvt_pk_bf16_f32 v60, v60, v113
	ds_write_b16 v249, v60 offset:1792
	s_waitcnt vmcnt(15)
	v_lshlrev_b32_e32 v60, 16, v107
	v_mul_f32_e32 v61, 0x3d372713, v60
	v_mul_f32_e32 v61, v61, v60
	v_fma_f32 v61, v61, v60, v60
	v_mul_f32_e32 v61, 0x3fcc422a, v61
	v_mul_f32_e32 v61, 0xbfb8aa3b, v61
	v_exp_f32_e32 v61, v61
	s_nop 0
	v_add_f32_e32 v61, 1.0, v61
	v_rcp_f32_e32 v61, v61
	v_fma_f32 v58, v110, v253, v181
	v_mul_f32_e32 v60, v61, v60
	v_mul_f32_e32 v58, v60, v58
	v_cvt_pk_bf16_f32 v58, v58, v113
	ds_write_b16 v249, v58 offset:1920
	v_lshl_add_u32 v163, v220, 4, s98
	v_add_u32_e32 v163, 0x800, v163
	s_waitcnt lgkmcnt(0)
	ds_read_b128 v[152:155], v163
	ds_read_b128 v[156:159], v163 offset:1024
	v_add_co_u32_e32 v160, vcc, 0x12000, v250
	s_nop 1
	v_addc_co_u32_e32 v161, vcc, 0, v251, vcc
	s_waitcnt lgkmcnt(0)
	global_store_dwordx4 v[250:251], v[152:155], off
	global_store_dwordx4 v[160:161], v[156:159], off
	s_waitcnt lgkmcnt(0)
	s_barrier
	s_cbranch_scc0 .LBB0_959
.LBB0_1094:
	s_lshl_b32 s15, s11, 7
	s_mov_b64 s[0:1], s[22:23]
	v_add_u32_e32 v82, s15, v130
	s_add_u32 s8, s0, 0x7a00000
	v_max_i32_e32 v56, 3, v82
	s_addc_u32 s9, s1, 0
	v_add_u32_e32 v112, -3, v56
	v_lshl_add_u64 v[56:57], s[20:21], 0, v[112:113]
	v_mov_b64_e32 v[72:73], s[8:9]
	v_mad_u64_u32 v[58:59], s[0:1], v56, s33, v[72:73]
	v_mad_i32_i24 v59, v57, s33, v59
	v_mov_b32_e32 v107, v113
	v_lshl_add_u64 v[56:57], v[58:59], 0, v[106:107]
	v_add_co_u32_e32 v56, vcc, s74, v56
	v_max_i32_e32 v74, -1, v82
	s_nop 0
	v_addc_co_u32_e32 v57, vcc, 0, v57, vcc
	s_waitcnt vmcnt(4)
	v_mov_b32_e32 v64, v228
	v_mov_b32_e32 v65, v229
	v_mov_b32_e32 v66, v230
	v_mov_b32_e32 v67, v231
	v_or_b32_e32 v56, 1, v82
	v_max_i32_e32 v56, 3, v56
	v_add_u32_e32 v112, -3, v56
	v_lshl_add_u64 v[56:57], s[20:21], 0, v[112:113]
	v_mad_u64_u32 v[58:59], s[0:1], v56, s33, v[72:73]
	v_mad_i32_i24 v59, v57, s33, v59
	v_lshl_add_u64 v[56:57], v[58:59], 0, v[106:107]
	v_add_co_u32_e32 v56, vcc, s74, v56
	v_cmp_lt_i32_e64 s[2:3], 2, v82
	s_nop 0
	v_addc_co_u32_e32 v57, vcc, 0, v57, vcc
	v_mov_b32_e32 v68, v232
	v_mov_b32_e32 v69, v233
	v_mov_b32_e32 v70, v234
	v_mov_b32_e32 v71, v235
	v_max_i32_e32 v56, 1, v82
	v_add_u32_e32 v112, -1, v56
	v_lshl_add_u64 v[56:57], s[20:21], 0, v[112:113]
	v_max_i32_e32 v112, 0, v82
	v_lshl_add_u64 v[60:61], s[20:21], 0, v[112:113]
	v_add_u32_e32 v112, 1, v74
	v_lshl_add_u64 v[74:75], s[20:21], 0, v[112:113]
	v_mad_u64_u32 v[58:59], s[0:1], v56, s33, v[72:73]
	v_mad_u64_u32 v[62:63], s[0:1], v60, s33, v[72:73]
	v_mad_u64_u32 v[72:73], s[0:1], v74, s33, v[72:73]
	v_mad_i32_i24 v73, v75, s33, v73
	v_lshl_add_u64 v[72:73], v[72:73], 0, v[106:107]
	v_add_co_u32_e64 v72, s[0:1], s74, v72
	v_mad_i32_i24 v59, v57, s33, v59
	s_nop 0
	v_addc_co_u32_e64 v73, s[0:1], 0, v73, s[0:1]
	v_mov_b32_e32 v72, v236
	v_mov_b32_e32 v73, v237
	v_mov_b32_e32 v74, v238
	v_mov_b32_e32 v75, v239
	v_lshl_add_u64 v[56:57], v[58:59], 0, v[106:107]
	v_add_co_u32_e32 v56, vcc, s74, v56
	v_mad_i32_i24 v63, v61, s33, v63
	s_nop 0
	v_addc_co_u32_e32 v57, vcc, 0, v57, vcc
	v_lshl_add_u64 v[60:61], v[62:63], 0, v[106:107]
	v_add_co_u32_e32 v60, vcc, s74, v60
	v_mov_b32_e32 v56, v240
	v_mov_b32_e32 v57, v241
	v_mov_b32_e32 v58, v242
	v_mov_b32_e32 v59, v243
	s_nop 0
	v_addc_co_u32_e32 v61, vcc, 0, v61, vcc
	v_mov_b32_e32 v60, v244
	v_mov_b32_e32 v61, v245
	v_mov_b32_e32 v62, v246
	v_mov_b32_e32 v63, v247
	v_cmp_lt_i32_e32 vcc, -2, v82
	v_cmp_lt_i32_e64 s[0:1], -1, v82
	s_nop 0
	v_cndmask_b32_e64 v83, 0, v67, s[2:3]
	v_cndmask_b32_e64 v64, 0, v64, s[2:3]
	s_nop 0
	v_cndmask_b32_e32 v107, 0, v72, vcc
	v_cndmask_b32_e32 v109, 0, v73, vcc
	v_cndmask_b32_e32 v112, 0, v74, vcc
	v_cndmask_b32_e32 v151, 0, v75, vcc
	v_cmp_lt_i32_e32 vcc, 1, v82
	v_lshlrev_b32_e32 v74, 16, v64
	v_lshlrev_b32_e32 v72, 16, v83
	v_cndmask_b32_e32 v67, 0, v68, vcc
	v_lshlrev_b32_e32 v75, 16, v67
	v_pk_mul_f32 v[76:77], v[104:105], v[74:75]
	v_cndmask_b32_e32 v84, 0, v71, vcc
	v_add_f32_e32 v68, v48, v76
	v_add_f32_e32 v74, v68, v77
	v_and_b32_e32 v77, 0xffff0000, v67
	v_and_b32_e32 v76, 0xffff0000, v64
	v_pk_mul_f32 v[80:81], v[40:41], v[76:77]
	v_cndmask_b32_e64 v67, 0, v65, s[2:3]
	v_add_f32_e32 v64, v49, v80
	v_cndmask_b32_e32 v71, 0, v69, vcc
	v_add_f32_e32 v152, v64, v81
	v_lshlrev_b32_e32 v65, 16, v71
	v_lshlrev_b32_e32 v64, 16, v67
	v_pk_mul_f32 v[68:69], v[100:101], v[64:65]
	v_lshlrev_b32_e32 v73, 16, v84
	v_add_f32_e32 v64, v50, v68
	v_add_f32_e32 v64, v64, v69
	v_and_b32_e32 v69, 0xffff0000, v71
	v_and_b32_e32 v68, 0xffff0000, v67
	v_pk_mul_f32 v[78:79], v[92:93], v[72:73]
	v_pk_mul_f32 v[80:81], v[42:43], v[68:69]
	v_add_f32_e32 v72, v54, v78
	v_add_f32_e32 v67, v51, v80
	v_cndmask_b32_e64 v78, 0, v66, s[2:3]
	v_cndmask_b32_e32 v80, 0, v70, vcc
	v_add_f32_e32 v153, v67, v81
	v_lshlrev_b32_e32 v67, 16, v80
	v_lshlrev_b32_e32 v66, 16, v78
	v_pk_mul_f32 v[70:71], v[96:97], v[66:67]
	v_cmp_lt_i32_e32 vcc, 0, v82
	v_add_f32_e32 v66, v52, v70
	v_add_f32_e32 v66, v66, v71
	v_and_b32_e32 v71, 0xffff0000, v80
	v_and_b32_e32 v70, 0xffff0000, v78
	v_pk_mul_f32 v[80:81], v[36:37], v[70:71]
	v_add_f32_e32 v72, v72, v79
	v_add_f32_e32 v78, v53, v80
	v_add_f32_e32 v154, v78, v81
	v_and_b32_e32 v79, 0xffff0000, v84
	v_and_b32_e32 v78, 0xffff0000, v83
	s_nop 0
	v_cndmask_b32_e64 v60, 0, v60, s[0:1]
	v_cndmask_b32_e32 v56, 0, v56, vcc
	v_pk_mul_f32 v[80:81], v[38:39], v[78:79]
	v_lshlrev_b32_e32 v84, 16, v56
	v_lshlrev_b32_e32 v85, 16, v60
	v_add_f32_e32 v80, v55, v80
	v_cndmask_b32_e64 v156, 0, v63, s[0:1]
	v_cndmask_b32_e32 v59, 0, v59, vcc
	v_pk_mul_f32 v[86:87], v[102:103], v[84:85]
	v_add_f32_e32 v155, v80, v81
	v_lshlrev_b32_e32 v80, 16, v59
	v_lshlrev_b32_e32 v81, 16, v156
	v_add_f32_e32 v63, v74, v86
	v_pk_mul_f32 v[82:83], v[90:91], v[80:81]
	v_add_f32_e32 v74, v63, v87
	v_and_b32_e32 v87, 0xffff0000, v60
	v_and_b32_e32 v86, 0xffff0000, v56
	v_add_f32_e32 v72, v72, v82
	v_pk_mul_f32 v[110:111], v[44:45], v[86:87]
	v_cndmask_b32_e64 v63, 0, v61, s[0:1]
	v_cndmask_b32_e32 v82, 0, v57, vcc
	v_add_f32_e32 v56, v152, v110
	v_lshlrev_b32_e32 v60, 16, v82
	v_lshlrev_b32_e32 v61, 16, v63
	v_add_f32_e32 v157, v56, v111
	v_pk_mul_f32 v[56:57], v[98:99], v[60:61]
	v_and_b32_e32 v111, 0xffff0000, v63
	v_add_f32_e32 v56, v64, v56
	v_and_b32_e32 v110, 0xffff0000, v82
	v_add_f32_e32 v64, v56, v57
	v_pk_mul_f32 v[56:57], v[46:47], v[110:111]
	v_cndmask_b32_e64 v82, 0, v62, s[0:1]
	v_cndmask_b32_e32 v58, 0, v58, vcc
	v_add_f32_e32 v56, v153, v56
	v_lshlrev_b32_e32 v62, 16, v58
	v_lshlrev_b32_e32 v63, 16, v82
	v_add_f32_e32 v158, v56, v57
	v_pk_mul_f32 v[56:57], v[94:95], v[62:63]
	v_and_b32_e32 v153, 0xffff0000, v82
	v_add_f32_e32 v56, v66, v56
	v_and_b32_e32 v152, 0xffff0000, v58
	v_add_f32_e32 v66, v56, v57
	v_pk_mul_f32 v[56:57], v[32:33], v[152:153]
	v_add_f32_e32 v72, v72, v83
	v_add_f32_e32 v56, v154, v56
	v_and_b32_e32 v83, 0xffff0000, v156
	v_and_b32_e32 v82, 0xffff0000, v59
	v_add_f32_e32 v58, v56, v57
	v_pk_mul_f32 v[56:57], v[34:35], v[82:83]
	s_add_u32 s0, s12, s15
	v_add_f32_e32 v56, v155, v56
	v_add_f32_e32 v59, v56, v57
	v_cvt_pk_bf16_f32 v56, v74, v157
	v_cvt_pk_bf16_f32 v57, v64, v158
	v_cvt_pk_bf16_f32 v58, v66, v58
	v_cvt_pk_bf16_f32 v59, v72, v59
	ds_write_b128 v142, v[56:59] offset:18432
	v_pk_mov_b32 v[56:57], v[74:75], v[84:85] op_sel:[1,0]
	v_and_b32_e32 v59, 0xffff0000, v107
	v_pk_mul_f32 v[56:57], v[104:105], v[56:57]
	v_and_b32_e32 v75, 0xffff0000, v151
	v_add_f32_e32 v56, v48, v56
	v_add_f32_e32 v58, v56, v57
	v_pk_mov_b32 v[56:57], v[76:77], v[86:87] op_sel:[1,0]
	s_addc_u32 s1, s13, 0
	v_pk_mul_f32 v[56:57], v[40:41], v[56:57]
	s_mulk_i32 s1, 0x2400
	v_add_f32_e32 v56, v49, v56
	v_add_f32_e32 v64, v56, v57
	v_pk_mov_b32 v[56:57], v[64:65], v[60:61] op_sel:[1,0]
	v_lshlrev_b32_e32 v65, 16, v109
	v_pk_mul_f32 v[56:57], v[100:101], v[56:57]
	s_mul_hi_u32 s2, s0, 0x2400
	v_add_f32_e32 v56, v50, v56
	v_add_f32_e32 v60, v56, v57
	v_pk_mov_b32 v[56:57], v[68:69], v[110:111] op_sel:[1,0]
	v_lshlrev_b32_e32 v69, 16, v112
	v_pk_mul_f32 v[56:57], v[42:43], v[56:57]
	s_add_i32 s2, s2, s1
	v_add_f32_e32 v56, v51, v56
	v_add_f32_e32 v68, v56, v57
	v_pk_mov_b32 v[56:57], v[66:67], v[62:63] op_sel:[1,0]
	v_and_b32_e32 v67, 0xffff0000, v109
	v_pk_mul_f32 v[56:57], v[96:97], v[56:57]
	v_mov_b32_e32 v66, v111
	v_add_f32_e32 v56, v52, v56
	v_add_f32_e32 v62, v56, v57
	v_pk_mov_b32 v[56:57], v[70:71], v[152:153] op_sel:[1,0]
	v_and_b32_e32 v71, 0xffff0000, v112
	v_pk_mul_f32 v[56:57], v[36:37], v[56:57]
	v_mov_b32_e32 v70, v153
	v_add_f32_e32 v56, v53, v56
	v_add_f32_e32 v72, v56, v57
	v_pk_mov_b32 v[56:57], v[72:73], v[80:81] op_sel:[1,0]
	v_lshlrev_b32_e32 v73, 16, v151
	v_pk_mul_f32 v[56:57], v[92:93], v[56:57]
	v_add_u32_e32 v80, v132, v131
	v_add_f32_e32 v56, v54, v56
	v_add_f32_e32 v74, v56, v57
	v_pk_mov_b32 v[56:57], v[78:79], v[82:83] op_sel:[1,0]
	s_mulk_i32 s0, 0x2400
	v_pk_mul_f32 v[56:57], v[38:39], v[56:57]
	s_add_u32 s0, s8, s0
	v_add_f32_e32 v56, v55, v56
	v_add_f32_e32 v76, v56, v57
	v_lshlrev_b32_e32 v57, 16, v107
	v_mov_b32_e32 v56, v85
	v_pk_mul_f32 v[56:57], v[102:103], v[56:57]
	s_addc_u32 s1, s9, s2
	v_add_f32_e32 v56, v58, v56
	v_mov_b32_e32 v58, v87
	v_add_f32_e32 v77, v56, v57
	v_pk_mul_f32 v[56:57], v[44:45], v[58:59]
	s_add_u32 s0, s0, s14
	v_add_f32_e32 v56, v64, v56
	v_mov_b32_e32 v64, v61
	v_add_f32_e32 v58, v56, v57
	v_pk_mul_f32 v[56:57], v[98:99], v[64:65]
	s_addc_u32 s1, s1, 0
	v_add_f32_e32 v56, v60, v56
	v_add_f32_e32 v59, v56, v57
	v_pk_mul_f32 v[56:57], v[46:47], v[66:67]
	v_mov_b32_e32 v109, v113
	v_add_f32_e32 v56, v68, v56
	v_mov_b32_e32 v68, v63
	v_add_f32_e32 v60, v56, v57
	v_pk_mul_f32 v[56:57], v[94:95], v[68:69]
	s_nop 0
	v_add_f32_e32 v56, v62, v56
	v_add_f32_e32 v61, v56, v57
	v_pk_mul_f32 v[56:57], v[32:33], v[70:71]
	s_nop 0
	v_add_f32_e32 v56, v72, v56
	v_mov_b32_e32 v72, v81
	v_add_f32_e32 v62, v56, v57
	v_pk_mul_f32 v[56:57], v[90:91], v[72:73]
	s_nop 0
	v_add_f32_e32 v56, v74, v56
	v_mov_b32_e32 v74, v83
	v_add_f32_e32 v63, v56, v57
	v_pk_mul_f32 v[56:57], v[34:35], v[74:75]
	s_nop 0
	v_add_f32_e32 v56, v76, v56
	v_add_f32_e32 v64, v56, v57
	v_cvt_pk_bf16_f32 v56, v77, v58
	v_cvt_pk_bf16_f32 v57, v59, v60
	v_cvt_pk_bf16_f32 v58, v61, v62
	v_cvt_pk_bf16_f32 v59, v63, v64
	ds_write_b128 v143, v[56:59] offset:18432
	s_waitcnt lgkmcnt(0)
	s_barrier
	s_add_i32 s98, s11, 1
	s_min_u32 s98, s98, 15
	s_lshl_b32 s98, s98, 7
	v_add_u32_e32 v172, s98, v130
	v_add_u32_e32 v173, 0x7a01c00, v106
	v_add_u32_e32 v174, -3, v172
	v_max_i32_e32 v174, 0, v174
	v_add_u32_e32 v174, s20, v174
	v_mad_u32_u24 v174, v174, s33, v173
	global_load_dwordx4 v[228:231], v174, s[22:23]
	v_add_u32_e32 v175, -2, v172
	v_max_i32_e32 v175, 0, v175
	v_add_u32_e32 v175, s20, v175
	v_mad_u32_u24 v175, v175, s33, v173
	global_load_dwordx4 v[232:235], v175, s[22:23]
	v_add_u32_e32 v176, 1, v172
	v_max_i32_e32 v176, 0, v176
	v_add_u32_e32 v176, s20, v176
	v_mad_u32_u24 v176, v176, s33, v173
	global_load_dwordx4 v[236:239], v176, s[22:23]
	v_add_u32_e32 v177, -1, v172
	v_max_i32_e32 v177, 0, v177
	v_add_u32_e32 v177, s20, v177
	v_mad_u32_u24 v177, v177, s33, v173
	global_load_dwordx4 v[240:243], v177, s[22:23]
	v_add_u32_e32 v178, 0, v172
	v_max_i32_e32 v178, 0, v178
	v_add_u32_e32 v178, s20, v178
	v_mad_u32_u24 v178, v178, s33, v173
	global_load_dwordx4 v[244:247], v178, s[22:23]
	ds_read_b128 v[56:59], v80 offset:18432
	ds_read_b128 v[60:63], v144
	ds_read_b128 v[68:71], v144 offset:2304
	ds_read_b128 v[76:79], v144 offset:4608
	ds_read_b128 v[72:75], v144 offset:11520
	s_waitcnt lgkmcnt(1)
	v_mfma_f32_16x16x32_bf16 v[152:155], v[76:79], v[56:59], 0
	ds_read_b128 v[76:79], v144 offset:13824
	ds_read_b128 v[64:67], v144 offset:9216
	s_waitcnt lgkmcnt(1)
	v_mfma_f32_16x16x32_bf16 v[156:159], v[76:79], v[56:59], 0
	ds_read_b128 v[76:79], v144 offset:6912
	s_waitcnt lgkmcnt(0)
	v_mfma_f32_16x16x32_bf16 v[160:163], v[76:79], v[56:59], 0
	ds_read_b128 v[76:79], v144 offset:16128
	v_mfma_f32_16x16x32_bf16 v[60:63], v[60:63], v[56:59], 0
	v_mfma_f32_16x16x32_bf16 v[64:67], v[64:67], v[56:59], 0
	v_mfma_f32_16x16x32_bf16 v[68:71], v[68:71], v[56:59], 0
	v_mfma_f32_16x16x32_bf16 v[72:75], v[72:75], v[56:59], 0
	s_waitcnt lgkmcnt(0)
	v_mfma_f32_16x16x32_bf16 v[164:167], v[76:79], v[56:59], 0
	ds_read_b128 v[168:171], v80 offset:18496
	ds_read_b128 v[56:59], v144 offset:64
	ds_read_b64 v[110:111], v145 offset:18432
	s_waitcnt lgkmcnt(1)
	v_mfma_f32_16x16x32_bf16 v[84:87], v[56:59], v[168:171], v[60:63]
	ds_read_b128 v[56:59], v144 offset:9280
	s_nop 1
	ds_read_b128 v[60:63], v144 offset:16192
	s_waitcnt lgkmcnt(1)
	v_mfma_f32_16x16x32_bf16 v[80:83], v[56:59], v[168:171], v[64:67]
	ds_read_b128 v[56:59], v144 offset:2368
	s_nop 0
	v_add_f32_e32 v84, v0, v84
	v_mul_f32_e32 v84, 0xbfb8aa3b, v84
	s_waitcnt lgkmcnt(0)
	v_mfma_f32_16x16x32_bf16 v[76:79], v[56:59], v[168:171], v[68:71]
	ds_read_b128 v[56:59], v144 offset:11584
	v_exp_f32_e32 v84, v84
	v_add_f32_e32 v80, v4, v80
	v_mul_f32_e32 v80, 0xbfb8aa3b, v80
	v_exp_f32_e32 v80, v80
	v_add_f32_e32 v84, 1.0, v84
	v_rcp_f32_e32 v107, v84
	s_waitcnt lgkmcnt(0)
	v_mfma_f32_16x16x32_bf16 v[72:75], v[56:59], v[168:171], v[72:75]
	ds_read_b128 v[56:59], v144 offset:4672
	v_add_f32_e32 v80, 1.0, v80
	v_mul_f32_e32 v107, v127, v107
	v_rcp_f32_e32 v84, v80
	v_mul_f32_e32 v80, 0x3fb8aa3b, v107
	v_add_f32_e32 v107, v107, v107
	v_mul_f32_e32 v107, 0x3fb8aa3b, v107
	v_add_f32_e32 v85, v1, v85
	v_exp_f32_e32 v107, v107
	v_mul_f32_e32 v85, 0xbfb8aa3b, v85
	v_exp_f32_e32 v85, v85
	v_add_f32_e32 v81, v5, v81
	v_sub_f32_e32 v107, 1.0, v107
	v_max_f32_e32 v107, 0, v107
	v_add_f32_e32 v85, 1.0, v85
	v_mul_f32_e32 v81, 0xbfb8aa3b, v81
	s_waitcnt lgkmcnt(0)
	v_mfma_f32_16x16x32_bf16 v[68:71], v[56:59], v[168:171], v[152:155]
	v_exp_f32_e32 v81, v81
	v_add_f32_e32 v86, v2, v86
	v_mul_f32_e32 v86, 0xbfb8aa3b, v86
	v_sqrt_f32_e32 v152, v107
	v_rcp_f32_e32 v107, v85
	v_add_f32_e32 v81, 1.0, v81
	v_rcp_f32_e32 v85, v81
	v_exp_f32_e32 v86, v86
	v_mul_f32_e32 v107, v126, v107
	v_mul_f32_e32 v81, 0x3fb8aa3b, v107
	v_add_f32_e32 v107, v107, v107
	v_mul_f32_e32 v107, 0x3fb8aa3b, v107
	v_exp_f32_e32 v107, v107
	v_add_f32_e32 v82, v6, v82
	v_add_f32_e32 v86, 1.0, v86
	v_mul_f32_e32 v82, 0xbfb8aa3b, v82
	v_sub_f32_e32 v107, 1.0, v107
	v_max_f32_e32 v107, 0, v107
	v_sqrt_f32_e32 v153, v107
	v_rcp_f32_e32 v107, v86
	v_exp_f32_e32 v82, v82
	v_add_f32_e32 v87, v3, v87
	v_mul_f32_e32 v87, 0xbfb8aa3b, v87
	v_mul_f32_e32 v107, v125, v107
	v_add_f32_e32 v82, 1.0, v82
	v_rcp_f32_e32 v86, v82
	v_mul_f32_e32 v82, 0x3fb8aa3b, v107
	v_add_f32_e32 v107, v107, v107
	v_mul_f32_e32 v107, 0x3fb8aa3b, v107
	v_exp_f32_e32 v107, v107
	v_exp_f32_e32 v87, v87
	v_add_f32_e32 v83, v7, v83
	v_mul_f32_e32 v83, 0xbfb8aa3b, v83
	v_sub_f32_e32 v107, 1.0, v107
	v_max_f32_e32 v107, 0, v107
	v_add_f32_e32 v87, 1.0, v87
	v_pk_mul_f32 v[84:85], v[84:85], v[152:153]
	v_sqrt_f32_e32 v152, v107
	v_rcp_f32_e32 v107, v87
	v_exp_f32_e32 v83, v83
	ds_read_b128 v[56:59], v144 offset:13888
	v_exp_f32_e32 v80, v80
	v_mul_f32_e32 v107, v124, v107
	v_add_f32_e32 v83, 1.0, v83
	v_rcp_f32_e32 v87, v83
	v_mul_f32_e32 v83, 0x3fb8aa3b, v107
	v_add_f32_e32 v107, v107, v107
	v_mul_f32_e32 v107, 0x3fb8aa3b, v107
	v_exp_f32_e32 v107, v107
	v_exp_f32_e32 v81, v81
	v_exp_f32_e32 v82, v82
	v_exp_f32_e32 v83, v83
	v_sub_f32_e32 v107, 1.0, v107
	v_max_f32_e32 v107, 0, v107
	v_sqrt_f32_e32 v153, v107
	v_add_f32_e32 v76, v8, v76
	v_add_f32_e32 v77, v9, v77
	v_mul_f32_e32 v76, 0xbfb8aa3b, v76
	v_mul_f32_e32 v77, 0xbfb8aa3b, v77
	v_exp_f32_e32 v76, v76
	v_exp_f32_e32 v77, v77
	v_lshlrev_b32_e32 v154, 16, v110
	v_and_b32_e32 v155, 0xffff0000, v110
	v_lshlrev_b32_e32 v110, 16, v111
	v_and_b32_e32 v111, 0xffff0000, v111
	v_pk_mul_f32 v[86:87], v[86:87], v[152:153]
	v_add_u32_e32 v107, v133, v137
	s_waitcnt lgkmcnt(0)
	v_mfma_f32_16x16x32_bf16 v[64:67], v[56:59], v[168:171], v[156:159]
	ds_read_b128 v[56:59], v144 offset:6976
	v_pk_mul_f32 v[84:85], v[84:85], v[154:155]
	v_pk_mul_f32 v[86:87], v[86:87], v[110:111]
	ds_write_b128 v107, v[80:83] offset:36864
	v_add_u32_e32 v80, v134, v137
	v_add_f32_e32 v78, v10, v78
	ds_write_b128 v80, v[84:87]
	v_add_f32_e32 v72, v12, v72
	v_add_f32_e32 v73, v13, v73
	v_mul_f32_e32 v78, 0xbfb8aa3b, v78
	ds_read_b64 v[80:81], v146 offset:18432
	v_add_f32_e32 v76, 1.0, v76
	v_mul_f32_e32 v72, 0xbfb8aa3b, v72
	v_add_f32_e32 v77, 1.0, v77
	v_mul_f32_e32 v73, 0xbfb8aa3b, v73
	v_exp_f32_e32 v78, v78
	v_rcp_f32_e32 v82, v76
	v_exp_f32_e32 v72, v72
	v_rcp_f32_e32 v83, v77
	v_exp_f32_e32 v73, v73
	v_add_f32_e32 v74, v14, v74
	v_add_f32_e32 v78, 1.0, v78
	v_mul_f32_e32 v74, 0xbfb8aa3b, v74
	v_add_f32_e32 v72, 1.0, v72
	v_mul_f32_e32 v82, v123, v82
	v_add_f32_e32 v73, 1.0, v73
	v_mul_f32_e32 v83, v122, v83
	s_waitcnt lgkmcnt(0)
	v_lshlrev_b32_e32 v84, 16, v80
	v_and_b32_e32 v85, 0xffff0000, v80
	v_rcp_f32_e32 v80, v78
	v_exp_f32_e32 v74, v74
	v_rcp_f32_e32 v76, v72
	v_mul_f32_e32 v72, 0x3fb8aa3b, v82
	v_add_f32_e32 v82, v82, v82
	v_rcp_f32_e32 v77, v73
	v_mul_f32_e32 v73, 0x3fb8aa3b, v83
	v_add_f32_e32 v83, v83, v83
	v_mul_f32_e32 v82, 0x3fb8aa3b, v82
	v_mul_f32_e32 v83, 0x3fb8aa3b, v83
	v_exp_f32_e32 v82, v82
	v_exp_f32_e32 v83, v83
	v_add_f32_e32 v74, 1.0, v74
	v_mul_f32_e32 v80, v121, v80
	v_rcp_f32_e32 v78, v74
	v_mul_f32_e32 v74, 0x3fb8aa3b, v80
	v_add_f32_e32 v80, v80, v80
	v_mul_f32_e32 v80, 0x3fb8aa3b, v80
	v_add_f32_e32 v79, v11, v79
	v_sub_f32_e32 v82, 1.0, v82
	v_sub_f32_e32 v83, 1.0, v83
	v_exp_f32_e32 v80, v80
	v_mul_f32_e32 v79, 0xbfb8aa3b, v79
	v_max_f32_e32 v82, 0, v82
	v_max_f32_e32 v83, 0, v83
	v_exp_f32_e32 v79, v79
	v_sqrt_f32_e32 v82, v82
	v_sqrt_f32_e32 v83, v83
	v_sub_f32_e32 v80, 1.0, v80
	v_add_f32_e32 v75, v15, v75
	v_max_f32_e32 v80, 0, v80
	v_add_f32_e32 v79, 1.0, v79
	v_mul_f32_e32 v75, 0xbfb8aa3b, v75
	v_pk_mul_f32 v[76:77], v[76:77], v[82:83]
	v_sqrt_f32_e32 v82, v80
	v_rcp_f32_e32 v80, v79
	v_exp_f32_e32 v75, v75
	v_exp_f32_e32 v72, v72
	v_exp_f32_e32 v73, v73
	v_mul_f32_e32 v80, v120, v80
	v_add_f32_e32 v75, 1.0, v75
	v_rcp_f32_e32 v79, v75
	v_mul_f32_e32 v75, 0x3fb8aa3b, v80
	v_add_f32_e32 v80, v80, v80
	v_mul_f32_e32 v80, 0x3fb8aa3b, v80
	v_exp_f32_e32 v80, v80
	v_exp_f32_e32 v74, v74
	v_exp_f32_e32 v75, v75
	v_add_f32_e32 v68, v16, v68
	v_sub_f32_e32 v80, 1.0, v80
	v_max_f32_e32 v80, 0, v80
	v_sqrt_f32_e32 v83, v80
	v_add_f32_e32 v69, v17, v69
	v_mul_f32_e32 v68, 0xbfb8aa3b, v68
	v_mul_f32_e32 v69, 0xbfb8aa3b, v69
	v_lshlrev_b32_e32 v80, 16, v81
	v_and_b32_e32 v81, 0xffff0000, v81
	v_pk_mul_f32 v[78:79], v[78:79], v[82:83]
	v_exp_f32_e32 v68, v68
	v_exp_f32_e32 v69, v69
	v_pk_mul_f32 v[78:79], v[78:79], v[80:81]
	v_add_u32_e32 v80, v133, v138
	v_pk_mul_f32 v[76:77], v[76:77], v[84:85]
	ds_write_b128 v80, v[72:75] offset:36864
	v_add_u32_e32 v72, v134, v138
	v_add_f32_e32 v70, v18, v70
	ds_write_b128 v72, v[76:79]
	v_add_f32_e32 v64, v20, v64
	v_add_f32_e32 v65, v21, v65
	v_mul_f32_e32 v70, 0xbfb8aa3b, v70
	ds_read_b64 v[72:73], v147 offset:18432
	v_add_f32_e32 v68, 1.0, v68
	v_mul_f32_e32 v64, 0xbfb8aa3b, v64
	v_add_f32_e32 v69, 1.0, v69
	v_mul_f32_e32 v65, 0xbfb8aa3b, v65
	v_exp_f32_e32 v70, v70
	v_rcp_f32_e32 v74, v68
	v_exp_f32_e32 v64, v64
	v_rcp_f32_e32 v75, v69
	v_exp_f32_e32 v65, v65
	v_add_f32_e32 v66, v22, v66
	v_add_f32_e32 v70, 1.0, v70
	v_mul_f32_e32 v66, 0xbfb8aa3b, v66
	v_add_f32_e32 v64, 1.0, v64
	v_mul_f32_e32 v74, v119, v74
	v_add_f32_e32 v65, 1.0, v65
	v_mul_f32_e32 v75, v118, v75
	s_waitcnt lgkmcnt(0)
	v_lshlrev_b32_e32 v76, 16, v72
	v_and_b32_e32 v77, 0xffff0000, v72
	v_rcp_f32_e32 v72, v70
	v_exp_f32_e32 v66, v66
	v_rcp_f32_e32 v68, v64
	v_mul_f32_e32 v64, 0x3fb8aa3b, v74
	v_add_f32_e32 v74, v74, v74
	v_rcp_f32_e32 v69, v65
	v_mul_f32_e32 v65, 0x3fb8aa3b, v75
	v_add_f32_e32 v75, v75, v75
	v_mul_f32_e32 v74, 0x3fb8aa3b, v74
	v_mul_f32_e32 v75, 0x3fb8aa3b, v75
	v_exp_f32_e32 v74, v74
	v_exp_f32_e32 v75, v75
	v_add_f32_e32 v66, 1.0, v66
	v_mul_f32_e32 v72, v117, v72
	v_rcp_f32_e32 v70, v66
	v_mul_f32_e32 v66, 0x3fb8aa3b, v72
	v_add_f32_e32 v72, v72, v72
	v_mul_f32_e32 v72, 0x3fb8aa3b, v72
	v_add_f32_e32 v71, v19, v71
	v_sub_f32_e32 v74, 1.0, v74
	v_sub_f32_e32 v75, 1.0, v75
	v_exp_f32_e32 v72, v72
	v_mul_f32_e32 v71, 0xbfb8aa3b, v71
	v_max_f32_e32 v74, 0, v74
	v_max_f32_e32 v75, 0, v75
	v_exp_f32_e32 v71, v71
	v_sqrt_f32_e32 v74, v74
	v_sqrt_f32_e32 v75, v75
	v_sub_f32_e32 v72, 1.0, v72
	v_add_f32_e32 v67, v23, v67
	v_max_f32_e32 v72, 0, v72
	v_add_f32_e32 v71, 1.0, v71
	v_mul_f32_e32 v67, 0xbfb8aa3b, v67
	v_pk_mul_f32 v[68:69], v[68:69], v[74:75]
	v_sqrt_f32_e32 v74, v72
	v_rcp_f32_e32 v72, v71
	v_exp_f32_e32 v67, v67
	v_mfma_f32_16x16x32_bf16 v[56:59], v[56:59], v[168:171], v[160:163]
	v_exp_f32_e32 v64, v64
	v_mul_f32_e32 v72, v116, v72
	v_add_f32_e32 v67, 1.0, v67
	v_rcp_f32_e32 v71, v67
	v_mul_f32_e32 v67, 0x3fb8aa3b, v72
	v_add_f32_e32 v72, v72, v72
	v_mul_f32_e32 v72, 0x3fb8aa3b, v72
	v_exp_f32_e32 v72, v72
	v_add_f32_e32 v56, v24, v56
	v_add_f32_e32 v57, v25, v57
	v_mul_f32_e32 v56, 0xbfb8aa3b, v56
	v_sub_f32_e32 v72, 1.0, v72
	v_max_f32_e32 v72, 0, v72
	v_mul_f32_e32 v57, 0xbfb8aa3b, v57
	v_sqrt_f32_e32 v75, v72
	v_exp_f32_e32 v56, v56
	v_exp_f32_e32 v57, v57
	v_exp_f32_e32 v65, v65
	v_exp_f32_e32 v66, v66
	v_exp_f32_e32 v67, v67
	v_add_f32_e32 v58, v26, v58
	v_mul_f32_e32 v58, 0xbfb8aa3b, v58
	v_lshlrev_b32_e32 v72, 16, v73
	v_and_b32_e32 v73, 0xffff0000, v73
	v_pk_mul_f32 v[70:71], v[70:71], v[74:75]
	v_add_f32_e32 v56, 1.0, v56
	v_add_f32_e32 v57, 1.0, v57
	v_exp_f32_e32 v58, v58
	v_pk_mul_f32 v[70:71], v[70:71], v[72:73]
	v_add_u32_e32 v72, v133, v139
	v_rcp_f32_e32 v56, v56
	v_rcp_f32_e32 v57, v57
	v_pk_mul_f32 v[68:69], v[68:69], v[76:77]
	ds_write_b128 v72, v[64:67] offset:36864
	v_add_u32_e32 v64, v134, v139
	v_mfma_f32_16x16x32_bf16 v[60:63], v[60:63], v[168:171], v[164:167]
	ds_write_b128 v64, v[68:71]
	ds_read_b64 v[64:65], v148 offset:18432
	v_add_f32_e32 v58, 1.0, v58
	v_mul_f32_e32 v66, v115, v56
	v_mul_f32_e32 v67, v114, v57
	v_rcp_f32_e32 v58, v58
	v_mul_f32_e32 v56, 0x3fb8aa3b, v66
	v_add_f32_e32 v66, v66, v66
	v_mul_f32_e32 v57, 0x3fb8aa3b, v67
	v_add_f32_e32 v67, v67, v67
	v_add_f32_e32 v60, v28, v60
	v_mul_f32_e32 v66, 0x3fb8aa3b, v66
	v_add_f32_e32 v61, v29, v61
	v_mul_f32_e32 v67, 0x3fb8aa3b, v67
	v_add_f32_e32 v59, v27, v59
	v_mul_f32_e32 v60, 0xbfb8aa3b, v60
	v_exp_f32_e32 v66, v66
	v_mul_f32_e32 v61, 0xbfb8aa3b, v61
	v_exp_f32_e32 v67, v67
	v_mul_f32_e32 v59, 0xbfb8aa3b, v59
	v_exp_f32_e32 v60, v60
	v_exp_f32_e32 v61, v61
	s_waitcnt lgkmcnt(0)
	v_lshlrev_b32_e32 v68, 16, v64
	v_and_b32_e32 v69, 0xffff0000, v64
	v_mul_f32_e32 v64, v89, v58
	v_exp_f32_e32 v59, v59
	v_mul_f32_e32 v58, 0x3fb8aa3b, v64
	v_add_f32_e32 v64, v64, v64
	v_mul_f32_e32 v64, 0x3fb8aa3b, v64
	v_sub_f32_e32 v66, 1.0, v66
	v_sub_f32_e32 v67, 1.0, v67
	v_exp_f32_e32 v64, v64
	v_add_f32_e32 v60, 1.0, v60
	v_max_f32_e32 v66, 0, v66
	v_add_f32_e32 v61, 1.0, v61
	v_max_f32_e32 v67, 0, v67
	v_add_f32_e32 v59, 1.0, v59
	v_rcp_f32_e32 v60, v60
	v_sqrt_f32_e32 v66, v66
	v_rcp_f32_e32 v61, v61
	v_sqrt_f32_e32 v67, v67
	v_rcp_f32_e32 v59, v59
	v_sub_f32_e32 v64, 1.0, v64
	v_max_f32_e32 v64, 0, v64
	v_pk_mul_f32 v[60:61], v[60:61], v[66:67]
	v_sqrt_f32_e32 v66, v64
	v_mul_f32_e32 v64, v128, v59
	v_mul_f32_e32 v59, 0x3fb8aa3b, v64
	v_add_f32_e32 v64, v64, v64
	v_add_f32_e32 v62, v30, v62
	v_add_f32_e32 v63, v31, v63
	v_mul_f32_e32 v64, 0x3fb8aa3b, v64
	v_mul_f32_e32 v62, 0xbfb8aa3b, v62
	v_mul_f32_e32 v63, 0xbfb8aa3b, v63
	v_exp_f32_e32 v64, v64
	v_exp_f32_e32 v62, v62
	v_exp_f32_e32 v63, v63
	v_exp_f32_e32 v56, v56
	v_sub_f32_e32 v64, 1.0, v64
	v_add_f32_e32 v62, 1.0, v62
	v_add_f32_e32 v63, 1.0, v63
	v_max_f32_e32 v64, 0, v64
	v_rcp_f32_e32 v62, v62
	v_rcp_f32_e32 v63, v63
	v_sqrt_f32_e32 v67, v64
	v_exp_f32_e32 v57, v57
	v_exp_f32_e32 v58, v58
	v_exp_f32_e32 v59, v59
	v_lshlrev_b32_e32 v64, 16, v65
	v_and_b32_e32 v65, 0xffff0000, v65
	v_pk_mul_f32 v[62:63], v[62:63], v[66:67]
	v_pk_mul_f32 v[60:61], v[60:61], v[68:69]
	v_pk_mul_f32 v[62:63], v[62:63], v[64:65]
	v_add_u32_e32 v64, v133, v140
	ds_write_b128 v64, v[56:59] offset:36864
	v_add_u32_e32 v56, v134, v140
	v_lshl_add_u64 v[66:67], s[0:1], 0, v[108:109]
	ds_write_b128 v56, v[60:63]
	v_add_co_u32_e32 v56, vcc, s16, v66
	s_waitcnt lgkmcnt(0)
	s_barrier
	s_nop 0
	v_addc_co_u32_e32 v57, vcc, 0, v67, vcc
	v_lshrrev_b32_e32 v162, 3, v220
	v_mul_u32_u24_e32 v162, 0x2400, v162
	v_and_b32_e32 v163, 7, v220
	v_lshl_add_u32 v162, v163, 4, v162
	v_lshlrev_b32_e32 v163, 1, v220
	v_sub_u32_e32 v162, v162, v163
	v_add_u32_e32 v162, 0x800, v162
	v_add_co_u32_e32 v250, vcc, v162, v66
	s_nop 1
	v_addc_co_u32_e32 v251, vcc, 0, v67, vcc
	global_load_dwordx4 v[152:155], v[250:251], off
	v_add_co_u32_e32 v160, vcc, 0x12000, v250
	s_nop 1
	v_addc_co_u32_e32 v161, vcc, 0, v251, vcc
	global_load_dwordx4 v[156:159], v[160:161], off
	ds_read_b32 v182, v149 offset:36864
	ds_read_b32 v166, v150
	ds_read_b32 v183, v149 offset:37136
	ds_read_b32 v167, v150 offset:272
	ds_read_b32 v184, v149 offset:37408
	ds_read_b32 v168, v150 offset:544
	ds_read_b32 v185, v149 offset:37680
	ds_read_b32 v169, v150 offset:816
	ds_read_b32 v186, v149 offset:37952
	ds_read_b32 v170, v150 offset:1088
	ds_read_b32 v187, v149 offset:38224
	ds_read_b32 v171, v150 offset:1360
	ds_read_b32 v188, v149 offset:38496
	ds_read_b32 v172, v150 offset:1632
	ds_read_b32 v189, v149 offset:38768
	ds_read_b32 v173, v150 offset:1904
	ds_read_b32 v208, v149 offset:39040
	ds_read_b32 v174, v150 offset:2176
	ds_read_b32 v209, v149 offset:39312
	ds_read_b32 v175, v150 offset:2448
	ds_read_b32 v210, v149 offset:39584
	ds_read_b32 v176, v150 offset:2720
	ds_read_b32 v211, v149 offset:39856
	ds_read_b32 v177, v150 offset:2992
	ds_read_b32 v212, v149 offset:40128
	ds_read_b32 v178, v150 offset:3264
	ds_read_b32 v213, v149 offset:40400
	ds_read_b32 v179, v150 offset:3536
	ds_read_b32 v252, v149 offset:40672
	ds_read_b32 v180, v150 offset:3808
	ds_read_b32 v253, v149 offset:40944
	ds_read_b32 v181, v150 offset:4080
	s_lshl_b32 s0, s11, 6
	s_and_b32 s0, s0, 64
	s_andn2_b64 vcc, exec, s[4:5]
	s_mov_b32 s1, s10
	s_waitcnt lgkmcnt(0)
	v_fma_f32 v166, 0, v182, v166
	v_fma_f32 v167, v166, v183, v167
	v_mul_f32_e32 v183, v182, v183
	v_fma_f32 v168, v167, v184, v168
	v_mul_f32_e32 v184, v183, v184
	v_fma_f32 v169, v168, v185, v169
	v_mul_f32_e32 v185, v184, v185
	v_fma_f32 v170, v169, v186, v170
	v_mul_f32_e32 v186, v185, v186
	v_fma_f32 v171, v170, v187, v171
	v_mul_f32_e32 v187, v186, v187
	v_fma_f32 v172, v171, v188, v172
	v_mul_f32_e32 v188, v187, v188
	v_fma_f32 v173, v172, v189, v173
	v_mul_f32_e32 v189, v188, v189
	v_fma_f32 v174, v173, v208, v174
	v_mul_f32_e32 v208, v189, v208
	v_fma_f32 v175, v174, v209, v175
	v_mul_f32_e32 v209, v208, v209
	v_fma_f32 v176, v175, v210, v176
	v_mul_f32_e32 v210, v209, v210
	v_fma_f32 v177, v176, v211, v177
	v_mul_f32_e32 v211, v210, v211
	v_fma_f32 v178, v177, v212, v178
	v_mul_f32_e32 v212, v211, v212
	v_fma_f32 v179, v178, v213, v179
	v_mul_f32_e32 v213, v212, v213
	v_fma_f32 v180, v179, v252, v180
	v_mul_f32_e32 v252, v213, v252
	v_fma_f32 v181, v180, v253, v181
	v_mul_f32_e32 v253, v252, v253
	ds_write_b32 v150, v166
	ds_write_b32 v150, v167 offset:272
	ds_write_b32 v149, v183 offset:37136
	ds_write_b32 v150, v168 offset:544
	ds_write_b32 v149, v184 offset:37408
	ds_write_b32 v150, v169 offset:816
	ds_write_b32 v149, v185 offset:37680
	ds_write_b32 v150, v170 offset:1088
	ds_write_b32 v149, v186 offset:37952
	ds_write_b32 v150, v171 offset:1360
	ds_write_b32 v149, v187 offset:38224
	ds_write_b32 v150, v172 offset:1632
	ds_write_b32 v149, v188 offset:38496
	ds_write_b32 v150, v173 offset:1904
	ds_write_b32 v149, v189 offset:38768
	ds_write_b32 v150, v174 offset:2176
	ds_write_b32 v149, v208 offset:39040
	ds_write_b32 v150, v175 offset:2448
	ds_write_b32 v149, v209 offset:39312
	ds_write_b32 v150, v176 offset:2720
	ds_write_b32 v149, v210 offset:39584
	ds_write_b32 v150, v177 offset:2992
	ds_write_b32 v149, v211 offset:39856
	ds_write_b32 v150, v178 offset:3264
	ds_write_b32 v149, v212 offset:40128
	ds_write_b32 v150, v179 offset:3536
	ds_write_b32 v149, v213 offset:40400
	ds_write_b32 v150, v180 offset:3808
	ds_write_b32 v149, v252 offset:40672
	ds_write_b32 v150, v181 offset:4080
	v_mov_b32_e32 v164, v253
	v_mov_b32_e32 v111, v181
	ds_write_b32 v149, v164 offset:40944
	ds_write_b32 v135, v164
	ds_write_b32 v136, v111
	s_waitcnt lgkmcnt(0)
	s_barrier
	ds_read_b32 v166, v150
	ds_read_b32 v182, v149 offset:36864
	ds_read_b32 v167, v150 offset:272
	ds_read_b32 v183, v149 offset:37136
	ds_read_b32 v168, v150 offset:544
	ds_read_b32 v184, v149 offset:37408
	ds_read_b32 v169, v150 offset:816
	ds_read_b32 v185, v149 offset:37680
	ds_read_b32 v170, v150 offset:1088
	ds_read_b32 v186, v149 offset:37952
	ds_read_b32 v171, v150 offset:1360
	ds_read_b32 v187, v149 offset:38224
	ds_read_b32 v172, v150 offset:1632
	ds_read_b32 v188, v149 offset:38496
	ds_read_b32 v173, v150 offset:1904
	ds_read_b32 v189, v149 offset:38768
	ds_read_b32 v174, v150 offset:2176
	ds_read_b32 v208, v149 offset:39040
	ds_read_b32 v175, v150 offset:2448
	ds_read_b32 v209, v149 offset:39312
	ds_read_b32 v176, v150 offset:2720
	ds_read_b32 v210, v149 offset:39584
	ds_read_b32 v177, v150 offset:2992
	ds_read_b32 v211, v149 offset:39856
	ds_read_b32 v178, v150 offset:3264
	ds_read_b32 v212, v149 offset:40128
	ds_read_b32 v179, v150 offset:3536
	ds_read_b32 v213, v149 offset:40400
	ds_read_b32 v180, v150 offset:3808
	ds_read_b32 v252, v149 offset:40672
	ds_read_b32 v181, v150 offset:4080
	ds_read_b32 v253, v149 offset:40944
	v_lshl_add_u32 v56, s0, 2, v129
	ds_read_b32 v110, v56
	s_cbranch_vccnz .LBB0_1096
	v_add_u32_e32 v57, 0xfffff800, v141
	ds_read_b32 v68, v57
	ds_read_b32 v69, v141
	ds_read_b32 v70, v57 offset:256
	ds_read_b32 v71, v141 offset:256
	ds_read_b32 v72, v57 offset:512
	ds_read_b32 v73, v141 offset:512
	ds_read_b32 v74, v57 offset:768
	ds_read_b32 v75, v141 offset:768
	ds_read_b32 v76, v57 offset:1024
	ds_read_b32 v77, v141 offset:1024
	ds_read_b32 v78, v57 offset:1280
	ds_read_b32 v79, v141 offset:1280
	ds_read_b32 v80, v57 offset:1536
	ds_read_b32 v81, v141 offset:1536
	s_waitcnt lgkmcnt(0)
	v_fma_f32 v110, v110, v68, v69
	s_cmp_eq_u32 s1, 1
	s_cbranch_scc1 .LBB0_1096
	v_fma_f32 v110, v110, v70, v71
	s_cmp_eq_u32 s1, 2
	s_cbranch_scc1 .LBB0_1096
	v_fma_f32 v110, v110, v72, v73
	s_cmp_eq_u32 s1, 3
	s_cbranch_scc1 .LBB0_1096
	v_fma_f32 v110, v110, v74, v75
	s_cmp_eq_u32 s1, 4
	s_cbranch_scc1 .LBB0_1096
	v_fma_f32 v110, v110, v76, v77
	s_cmp_eq_u32 s1, 5
	s_cbranch_scc1 .LBB0_1096
	v_fma_f32 v110, v110, v78, v79
	s_cmp_eq_u32 s1, 6
	s_cbranch_scc1 .LBB0_1096
	v_fma_f32 v110, v110, v80, v81
